# arrive-only grid barriers 3-5: the closing workgroup barrier is dropped, so the other seven waves start the next phase while wave 0 finishes the arrival
# baseline (speedup 1.0000x reference)
.LBB0_295:
	s_or_b64 exec, exec, s[0:1]
	v_mov_b32_e32 v12, v0
	s_waitcnt lgkmcnt(0)
	s_mov_b64 s[100:101], exec
	v_readlane_b32 s98, v254, 6
	s_nop 3
	s_mov_b32 exec_lo, s98
	s_mov_b32 exec_hi, 0
	s_cbranch_execz .Lp3dep_join
	s_and_b32 s98, s64, 127
	s_lshr_b32 s98, s98, 1
	s_max_u32 s99, s98, 1
	s_add_i32 s99, s99, -1
	s_lshl_b32 s98, s98, 8
	s_lshl_b32 s99, s99, 8
	s_add_i32 s98, s98, 0x8000
	s_add_i32 s99, s99, 0x8000
	v_mov_b32_e32 v240, s98
	v_mov_b32_e32 v241, s99
	v_mov_b32_e32 v244, 0
	v_readfirstlane_b32 s98, v250
	v_readfirstlane_b32 s99, v251
	s_nop 3
	s_cmp_lt_u32 s98, 6
	s_cbranch_scc1 .Lp3dep_spin
	s_cmp_ge_u32 s99, 6
	s_cbranch_scc1 .Lp3dep_join

.LBB0_480:
	s_or_b64 exec, exec, s[0:1]
	v_mov_b32_e32 v184, v0
	s_waitcnt lgkmcnt(0)
	s_mov_b32 s98, 0
	s_nop 0
	v_readfirstlane_b32 s54, v184
	s_ashr_i32 s0, s54, 6
	s_cmpk_gt_i32 s64, 0x7f
	v_writelane_b32 v254, s0, 27
	s_cselect_b64 s[0:1], -1, 0
	v_writelane_b32 v254, s0, 35
	v_and_b32_e32 v183, 63, v184
	s_and_b64 vcc, exec, s[0:1]
	v_writelane_b32 v254, s1, 36
	s_cbranch_vccz .LBB0_497
	s_cmpk_gt_u32 s64, 0x8f
	s_mov_b64 s[2:3], -1
	v_writelane_b32 v254, s54, 54
	s_cbranch_scc1 .LBB0_498
	s_mov_b64 s[4:5], 0
	s_andn2_b64 vcc, exec, s[2:3]
	s_mov_b64 s[0:1], 0
	s_cbranch_vccz .LBB0_580

.LBB0_829:
	s_or_b64 exec, exec, s[0:1]
	v_mov_b32_e32 v194, v0
	v_readlane_b32 s2, v254, 35
	s_waitcnt lgkmcnt(0)
	v_readlane_b32 s3, v254, 36
	v_readfirstlane_b32 s56, v194
	v_and_b32_e32 v195, 63, v194
	s_ashr_i32 s33, s56, 6
	s_mov_b64 s[0:1], -1
	s_and_b64 vcc, exec, s[2:3]
	s_cbranch_vccz .LBB0_871
	s_add_i32 s0, s64, 0xffffff80
	s_lshl_b32 s1, s64, 6
	s_and_b32 s1, s1, 0x1c0
	s_lshr_b32 s2, s0, 3
	s_add_i32 s87, s2, s1
	s_bfe_u32 s4, s56, 0x20006
	v_lshrrev_b32_e32 v196, 3, v195
	v_lshrrev_b32_e32 v6, 5, v195
	v_lshrrev_b32_e32 v12, 1, v194
	v_lshl_or_b32 v5, s4, 3, v196
	s_cmp_lt_u32 s33, 4
	v_lshrrev_b32_e32 v2, 2, v195
	v_bfe_u32 v13, v194, 1, 3
	v_bitop3_b32 v12, v12, v6, 7 bitop3:0x6c
	v_and_b32_e32 v3, 4, v2
	v_bfe_u32 v4, v5, 1, 3
	s_cselect_b64 vcc, -1, 0
	v_lshlrev_b32_e32 v8, 3, v195
	v_lshlrev_b32_e32 v9, 2, v6
	v_and_b32_e32 v11, 16, v194
	v_lshlrev_b32_e32 v199, 2, v195
	v_lshlrev_b32_e32 v200, 4, v12
	v_bitop3_b32 v12, v6, v13, 2 bitop3:0x36
	v_cndmask_b32_e32 v3, v3, v4, vcc
	v_and_b32_e32 v197, 31, v194
	v_lshlrev_b32_e32 v4, 3, v6
	v_and_b32_e32 v8, 64, v8
	v_and_or_b32 v2, v2, 3, v9
	v_and_or_b32 v11, v199, 12, v11
	v_lshlrev_b32_e32 v201, 4, v12
	v_bitop3_b32 v12, v6, v13, 4 bitop3:0x36
	v_bitop3_b32 v6, v6, v13, 6 bitop3:0x36
	v_lshl_or_b32 v8, v11, 1, v8
	v_lshlrev_b32_e32 v203, 4, v6
	v_lshlrev_b32_e32 v2, 7, v2
	v_or_b32_e32 v6, 0x80, v197
	s_mov_b32 s3, 0x6000000
	s_and_b64 s[0:1], vcc, exec
	v_or_b32_e32 v204, v8, v2
	v_bitop3_b32 v205, v8, 64, v2 bitop3:0x36
	v_sub_u32_e32 v2, v6, v9
	s_cselect_b32 s0, s3, 0x7000000
	s_lshl_b32 s5, s4, 10
	v_subrev_u32_e32 v6, 27, v2
	s_movk_i32 s4, 0x81
	v_writelane_b32 v254, s56, 48
	v_cmp_gt_u32_e64 s[6:7], s4, v6
	v_subrev_u32_e32 v6, 26, v2
	s_lshl_b32 s1, s33, 10
	v_writelane_b32 v254, s6, 27
	s_and_b32 s3, s1, 0xfffff000
	v_lshlrev_b32_e32 v202, 4, v12
	v_writelane_b32 v254, s7, 28
	v_cmp_gt_u32_e64 s[6:7], s4, v6
	v_subrev_u32_e32 v6, 25, v2
	s_movk_i32 s1, 0x82
	v_writelane_b32 v254, s6, 29
	v_sub_u32_e32 v12, v197, v9
	v_cmp_gt_u32_e64 s[30:31], s1, v2
	v_writelane_b32 v254, s7, 30
	v_cmp_gt_u32_e64 s[6:7], s4, v6
	v_subrev_u32_e32 v6, 24, v2
	v_cmp_gt_u32_e64 s[34:35], s4, v2
	v_writelane_b32 v254, s6, 31
	s_add_i32 s89, s33, 1
	s_add_i32 s90, s33, 2
	v_writelane_b32 v254, s7, 32
	v_cmp_gt_u32_e64 s[6:7], s4, v6
	v_subrev_u32_e32 v6, 19, v2
	v_cmp_gt_u32_e64 s[10:11], s4, v6
	v_subrev_u32_e32 v6, 18, v2
	v_cmp_gt_u32_e64 s[12:13], s4, v6
	v_subrev_u32_e32 v6, 17, v2
	v_cmp_gt_u32_e64 s[14:15], s4, v6
	v_add_u32_e32 v6, -16, v2
	v_cmp_gt_u32_e64 s[16:17], s4, v6
	v_add_u32_e32 v6, -11, v2
	v_cmp_gt_u32_e64 s[18:19], s4, v6
	v_add_u32_e32 v6, -10, v2
	v_cmp_gt_u32_e64 s[20:21], s4, v6
	v_add_u32_e32 v6, -9, v2
	v_cmp_gt_u32_e64 s[22:23], s4, v6
	v_add_u32_e32 v6, -8, v2
	v_cmp_gt_u32_e64 s[24:25], s4, v6
	v_add_u32_e32 v6, -3, v2
	v_cmp_gt_u32_e64 s[26:27], s4, v6
	v_add_u32_e32 v6, -2, v2
	v_subrev_u32_e32 v2, 27, v12
	v_cmp_gt_u32_e64 s[36:37], s4, v2
	v_subrev_u32_e32 v2, 26, v12
	v_cmp_gt_u32_e64 s[38:39], s4, v2
	v_subrev_u32_e32 v2, 25, v12
	v_cmp_gt_u32_e64 s[40:41], s4, v2
	v_subrev_u32_e32 v2, 24, v12
	s_add_i32 s91, s33, 3
	s_add_i32 s92, s33, 4
	v_cmp_gt_u32_e64 s[42:43], s4, v2
	v_subrev_u32_e32 v2, 19, v12
	s_lshl_b32 s88, s33, 5
	s_lshl_b32 s8, s33, 13
	s_lshl_b32 s9, s89, 13
	s_lshl_b32 s54, s90, 13
	s_lshl_b32 s55, s91, 13
	s_lshl_b32 s56, s92, 13
	v_cmp_gt_u32_e64 s[44:45], s4, v2
	v_subrev_u32_e32 v2, 18, v12
	v_cmp_gt_u32_e64 s[46:47], s4, v2
	v_subrev_u32_e32 v2, 17, v12
	s_add_u32 s0, s82, s0
	v_cmp_gt_u32_e64 s[48:49], s4, v2
	v_add_u32_e32 v2, -16, v12
	s_addc_u32 s1, s83, 0
	v_bitop3_b32 v7, v3, v194, 7 bitop3:0x78
	v_cmp_gt_u32_e64 s[50:51], s4, v2
	v_add_u32_e32 v2, -11, v12
	s_add_u32 s93, s82, 0x5000000
	v_and_b32_e32 v10, 7, v194
	v_mov_b32_e32 v3, 0
	v_cmp_gt_u32_e64 s[52:53], s4, v2
	v_lshlrev_b32_e32 v2, 4, v7
	s_addc_u32 s94, s83, 0
	v_writelane_b32 v254, s6, 33
	v_cmp_gt_u32_e64 s[28:29], s4, v6
	s_mul_i32 s57, s33, 0x1300
	v_lshlrev_b32_e32 v6, 4, v10
	v_lshl_add_u64 v[178:179], s[0:1], 0, v[2:3]
	s_add_u32 s0, s82, 0x3000000
	v_mov_b32_e32 v7, v3
	v_writelane_b32 v254, s7, 34
	s_addc_u32 s1, s83, 0
	v_lshl_add_u64 v[8:9], s[82:83], 0, v[6:7]
	s_mov_b64 s[6:7], 0x2000000
	s_add_i32 s71, s57, 0
	v_lshl_add_u64 v[182:183], v[8:9], 0, s[6:7]
	s_mov_b64 s[6:7], 0x8000000
	s_add_i32 s95, s8, 0
	s_add_i32 s96, s9, 0
	s_add_i32 s97, s54, 0
	s_add_i32 s86, s55, 0
	s_add_i32 s70, s56, 0
	s_add_i32 s71, s71, 0x18000
	v_lshl_add_u64 v[184:185], v[8:9], 0, s[6:7]
	s_add_u32 s6, s82, 0x19800
	s_addc_u32 s7, s83, 0
	v_writelane_b32 v254, s6, 44
	s_movk_i32 s58, 0x90
	v_mov_b32_e32 v2, s71
	v_writelane_b32 v254, s7, 45
	s_and_b32 s6, s64, 7
	s_lshl_b32 s6, s6, 14
	s_lshl_b32 s2, s2, 8
	v_lshlrev_b32_e32 v11, 7, v197
	v_add_u32_e32 v13, -10, v12
	v_mad_u32_u24 v8, v197, s58, v2
	s_add_i32 s2, s6, s2
	v_or_b32_e32 v206, 8, v196
	v_or_b32_e32 v207, 16, v196
	v_or_b32_e32 v208, 24, v196
	v_readlane_b32 s6, v254, 24
	v_lshlrev_b32_e32 v2, 5, v10
	v_cmp_gt_u32_e64 s[54:55], s4, v13
	v_add_u32_e32 v9, -9, v12
	v_add_u32_e32 v13, -8, v12
	v_add_u32_e32 v14, -3, v12
	v_add_u32_e32 v15, -2, v12
	v_add_u32_e32 v16, -1, v12
	v_mul_u32_u24_e32 v17, 0x90, v196
	v_lshlrev_b32_e32 v18, 2, v196
	v_lshlrev_b32_e32 v19, 2, v206
	v_lshlrev_b32_e32 v20, 2, v207
	v_lshlrev_b32_e32 v21, 2, v208
	v_readlane_b32 s7, v254, 25
	v_add_u32_e32 v209, s95, v11
	v_lshl_add_u64 v[188:189], s[74:75], 0, v[2:3]
	v_add_u32_e32 v2, s71, v6
	s_or_b32 s3, s3, s5
	v_bfe_u32 v198, v195, 3, 2
	v_lshl_add_u64 v[180:181], s[76:77], 0, v[6:7]
	v_lshl_add_u64 v[186:187], s[6:7], 0, v[6:7]
	v_add_u32_e32 v210, s96, v11
	v_add_u32_e32 v211, s97, v11
	v_add_u32_e32 v212, s86, v11
	v_or_b32_e32 v213, 0xffffff80, v5
	s_add_i32 s3, s3, 0
	v_lshlrev_b32_e32 v190, 1, v4
	v_add_u32_e32 v214, v8, v4
	v_add_u32_e32 v215, v2, v17
	v_add_u32_e32 v216, s71, v18
	v_mov_b32_e32 v217, 0x358637bd
	v_add_u32_e32 v218, s71, v19
	v_add_u32_e32 v219, s71, v20
	v_add_u32_e32 v220, s71, v21
	v_mov_b32_e32 v191, v3
	v_add_u32_e32 v221, v209, v203
	v_mbcnt_hi_u32_b32 v222, -1, v1
	v_mov_b32_e32 v223, 0xf149f2ca
	v_cmp_gt_u32_e64 s[56:57], s4, v9
	v_cmp_gt_u32_e64 s[58:59], s4, v13
	v_cmp_gt_u32_e64 s[60:61], s4, v14
	v_cmp_gt_u32_e64 s[62:63], s4, v15
	v_cmp_gt_u32_e64 s[64:65], s4, v16
	v_cmp_gt_u32_e64 s[66:67], s4, v12
	s_mov_b32 s4, 0x80000
	s_mov_b32 s5, 0x3fb8aa3b
	s_mov_b32 s6, 0
	s_mov_b32 s75, 0
	v_cmp_gt_u32_e64 s[68:69], 32, v195
	s_branch .LBB0_832
